# ssd_local: C fragments of both mt iterations prefetched at the unit head
# baseline (speedup 1.0000x reference)
; __device__ __forceinline__ float bf2f(bf16_t v) { return __uint_as_float(((unsigned)v) << 16); }
; __device__ __forceinline__ float softplus_(float x) { return fmaxf(x, 0.f) + log1pf(__expf(-fabsf(x))); }
; __device__ void ssd_local_unit(const Params& p, unsigned char* smem, int unit) {
;     ...
;   if (tid < 128) {
;     const float raw = bf2f(proj[(size_t)(t0 + tid) * LDP + 4608 + hh]);
;     const float dtv = softplus_(raw + p.ssd_dt_bias[hh]);
;     dts[tid] = dtv;
;     adt[tid] = -__expf(p.ssd_a_log[hh]) * dtv;
;   }
;     ...
;     const int M = wid * 2 + mt;
;     const int lrow = M * 16 + l15;
;     bf16x8 cf[4];
; #pragma unroll
;     for (int ks = 0; ks < 4; ++ks) cf[ks] = cfrag(p, proj, t0 + lrow, ts0 + lrow, g, ks * 32 + q4 * 8);
.LBB0_612:
	v_add_u32_e32 v45, s33, v165
	v_lshlrev_b32_e32 v2, 3, v45
	v_bfe_u32 v47, v45, 4, 4
	v_and_b32_e32 v2, 0xfffff800, v2
	v_and_b32_e32 v50, 15, v45
	v_lshl_or_b32 v30, v47, 7, v2
	v_lshlrev_b32_e32 v232, 5, v50
	v_and_b32_e32 v232, 0x100, v232
	v_mov_b32_e32 v233, 0
	v_lshl_add_u64 v[232:233], v[40:41], 0, v[232:233]
	v_lshl_or_b32 v234, v74, 4, v1
	v_or_b32_e32 v234, v234, v30
	v_ashrrev_i32_e32 v235, 31, v234
	v_lshlrev_b64 v[234:235], 9, v[234:235]
	v_lshl_add_u64 v[234:235], v[232:233], 0, v[234:235]
	global_load_dwordx4 v[168:171], v[234:235], off
	global_load_dwordx4 v[172:175], v[234:235], off offset:64
	global_load_dwordx4 v[176:179], v[234:235], off offset:128
	global_load_dwordx4 v[180:183], v[234:235], off offset:192
	v_or_b32_e32 v236, 1, v74
	v_lshl_or_b32 v236, v236, 4, v1
	v_or_b32_e32 v236, v236, v30
	v_ashrrev_i32_e32 v237, 31, v236
	v_lshlrev_b64 v[236:237], 9, v[236:237]
	v_lshl_add_u64 v[236:237], v[232:233], 0, v[236:237]
	global_load_dwordx4 v[184:187], v[236:237], off
	global_load_dwordx4 v[188:191], v[236:237], off offset:64
	global_load_dwordx4 v[192:195], v[236:237], off offset:128
	global_load_dwordx4 v[196:199], v[236:237], off offset:192
	v_or_b32_sdwa v4, v30, v139 dst_sel:DWORD dst_unused:UNUSED_PAD src0_sel:DWORD src1_sel:BYTE_0
	v_lshlrev_b32_e32 v2, 2, v50
	s_and_saveexec_b64 s[22:23], s[4:5]
	s_cbranch_execz .LBB0_614
	v_mov_b64_e32 v[6:7], s[34:35]
	v_mad_i64_i32 v[6:7], s[12:13], v4, s43, v[6:7]
	v_lshlrev_b32_e32 v8, 1, v50
	v_mov_b32_e32 v9, v35
	v_lshl_add_u64 v[6:7], v[6:7], 0, v[8:9]
	v_add_co_u32_e32 v6, vcc, 0x4002000, v6
	s_nop 1
	v_addc_co_u32_e32 v7, vcc, 0, v7, vcc
	global_load_ushort v3, v[6:7], off offset:1024
	global_load_dword v5, v2, s[60:61]
	s_nop 0
	global_load_dword v6, v2, s[62:63]
	s_waitcnt vmcnt(2)
	v_lshlrev_b32_e32 v3, 16, v3
	s_waitcnt vmcnt(1)
	v_add_f32_e32 v3, v5, v3
	v_mul_f32_e64 v5, |v3|, s44
	v_exp_f32_e32 v5, v5
	s_waitcnt vmcnt(0)
	v_mul_f32_e32 v6, 0x3fb8aa3b, v6
	v_exp_f32_e32 v8, v6
	v_max_f32_e32 v3, 0, v3
	v_add_f32_e32 v9, 1.0, v5
	v_add_f32_e32 v10, -1.0, v9
	v_frexp_mant_f32_e32 v11, v9
	v_cvt_f64_f32_e32 v[6:7], v9
	v_sub_f32_e32 v12, v10, v9
	v_frexp_exp_i32_f64_e32 v6, v[6:7]
	v_cmp_gt_f32_e32 vcc, s45, v11
	v_sub_f32_e32 v10, v5, v10
	v_add_f32_e32 v7, 1.0, v12
	v_subbrev_co_u32_e32 v6, vcc, 0, v6, vcc
	v_add_f32_e32 v7, v10, v7
	v_sub_u32_e32 v10, 0, v6
	v_cvt_f32_i32_e32 v6, v6
	v_ldexp_f32 v9, v9, v10
	v_ldexp_f32 v7, v7, v10
	v_add_f32_e32 v10, -1.0, v9
	v_add_f32_e32 v11, 1.0, v9
	v_add_f32_e32 v12, 1.0, v10
	v_add_f32_e32 v13, -1.0, v11
	v_sub_f32_e32 v12, v9, v12
	v_sub_f32_e32 v9, v9, v13
	v_mul_f32_e32 v13, 0x3f317218, v6
	v_add_f32_e32 v12, v7, v12
	v_add_f32_e32 v7, v7, v9
	v_fma_f32 v9, v6, s46, -v13
	v_add_f32_e32 v14, v10, v12
	v_add_f32_e32 v15, v11, v7
	v_fmac_f32_e32 v9, 0xb102e308, v6
	v_sub_f32_e32 v6, v14, v10
	v_sub_f32_e32 v10, v15, v11
	v_rcp_f32_e32 v11, v15
	v_add_f32_e32 v16, v13, v9
	v_sub_f32_e32 v7, v7, v10
	v_sub_f32_e32 v10, v16, v13
	v_sub_f32_e32 v9, v9, v10
	v_mul_f32_e32 v10, v14, v11
	v_sub_f32_e32 v6, v12, v6
	v_mul_f32_e32 v12, v15, v10
	v_fma_f32 v13, v10, v15, -v12
	v_fmac_f32_e32 v13, v10, v7
	v_add_f32_e32 v17, v12, v13
	v_sub_f32_e32 v18, v14, v17
	v_sub_f32_e32 v12, v17, v12
	v_sub_f32_e32 v14, v14, v18
	v_sub_f32_e32 v12, v12, v13
	v_sub_f32_e32 v13, v14, v17
	v_add_f32_e32 v6, v6, v13
	v_add_f32_e32 v6, v12, v6
	v_add_f32_e32 v12, v18, v6
	v_mul_f32_e32 v13, v11, v12
	v_sub_f32_e32 v14, v18, v12
	v_mul_f32_e32 v17, v15, v13
	v_add_f32_e32 v6, v6, v14
	v_add_f32_e32 v14, v10, v13
	v_fma_f32 v15, v13, v15, -v17
	v_sub_f32_e32 v10, v14, v10
	v_fmac_f32_e32 v15, v13, v7
	v_sub_f32_e32 v7, v13, v10
	v_add_f32_e32 v10, v17, v15
	v_sub_f32_e32 v13, v10, v17
	v_sub_f32_e32 v17, v12, v10
	v_sub_f32_e32 v12, v12, v17
	v_sub_f32_e32 v10, v12, v10
	v_sub_f32_e32 v13, v13, v15
	v_add_f32_e32 v6, v6, v10
	v_add_f32_e32 v6, v13, v6
	v_add_f32_e32 v6, v17, v6
	v_mul_f32_e32 v6, v11, v6
	v_add_f32_e32 v6, v7, v6
	v_add_f32_e32 v7, v14, v6
	v_mul_f32_e32 v10, v7, v7
	v_fmamk_f32 v13, v10, 0x3e9b6dac, v103
	v_sub_f32_e32 v11, v7, v14
	v_ldexp_f32 v12, v7, 1
	v_mul_f32_e32 v7, v7, v10
	v_fmaak_f32 v10, v10, v13, 0x3f2aaada
	v_mul_f32_e32 v7, v7, v10
	v_add_f32_e32 v10, v12, v7
	v_sub_f32_e32 v6, v6, v11
	v_sub_f32_e32 v11, v10, v12
	v_ldexp_f32 v6, v6, 1
	v_sub_f32_e32 v7, v7, v11
	v_add_f32_e32 v6, v6, v7
	v_add_f32_e32 v7, v10, v6
	v_sub_f32_e32 v10, v7, v10
	v_add_f32_e32 v11, v16, v7
	v_sub_f32_e32 v6, v6, v10
	v_sub_f32_e32 v10, v11, v16
	v_sub_f32_e32 v12, v11, v10
	v_sub_f32_e32 v7, v7, v10
	v_add_f32_e32 v10, v9, v6
	v_sub_f32_e32 v12, v16, v12
	v_sub_f32_e32 v13, v10, v9
	v_add_f32_e32 v7, v7, v12
	v_sub_f32_e32 v12, v10, v13
	v_sub_f32_e32 v6, v6, v13
	v_sub_f32_e32 v9, v9, v12
	v_add_f32_e32 v7, v10, v7
	v_add_f32_e32 v6, v6, v9
	v_add_f32_e32 v9, v11, v7
	v_sub_f32_e32 v10, v9, v11
	v_sub_f32_e32 v7, v7, v10
	v_add_f32_e32 v6, v6, v7
	v_add_f32_e32 v6, v9, v6
	v_cmp_neq_f32_e32 vcc, s47, v5
	s_nop 1
	v_cndmask_b32_e32 v6, v116, v6, vcc
	v_cmp_ngt_f32_e32 vcc, -1.0, v5
	s_nop 1
	v_cndmask_b32_e32 v6, v117, v6, vcc
	v_cmp_neq_f32_e32 vcc, -1.0, v5
	s_nop 1
	v_cndmask_b32_e32 v6, v118, v6, vcc
	v_cmp_lt_f32_e64 vcc, |v5|, s48
	s_nop 1
	v_cndmask_b32_e32 v5, v6, v5, vcc
	v_add_f32_e32 v3, v3, v5
	ds_write_b32 v55, v3
	v_mul_f32_e64 v3, v3, -v8
	ds_write_b32 v56, v3

; __device__ void ssd_local_unit(const Params& p, unsigned char* smem, int unit) {
;     ...
;   for (int mt = 0; mt < 2; ++mt) {
;     const int M = wid * 2 + mt;
;     const int lrow = M * 16 + l15;
;     bf16x8 cf[4];
; #pragma unroll
;     for (int ks = 0; ks < 4; ++ks) cf[ks] = cfrag(p, proj, t0 + lrow, ts0 + lrow, g, ks * 32 + q4 * 8);
;     const float acl = acs[lrow];
;     const int ntmax = M | 1;
.LBB0_627:
	v_or_b32_e32 v32, s3, v74
	v_lshl_or_b32 v33, v32, 4, v1
	v_or_b32_e32 v28, v33, v30
	v_ashrrev_i32_e32 v29, 31, v28
	v_lshlrev_b64 v[2:3], 9, v[28:29]
	v_lshl_add_u64 v[14:15], v[22:23], 0, v[2:3]
	s_cmp_eq_u32 s3, 0
	s_cbranch_scc0 .Lssd_c1
	v_mov_b64 v[2:3], v[168:169]
	v_mov_b64 v[4:5], v[170:171]
	v_mov_b64 v[6:7], v[172:173]
	v_mov_b64 v[8:9], v[174:175]
	v_mov_b64 v[10:11], v[176:177]
	v_mov_b64 v[12:13], v[178:179]
	v_mov_b64 v[14:15], v[180:181]
	v_mov_b64 v[16:17], v[182:183]
	s_branch .Lssd_cdone
.Lssd_c1:
	v_mov_b64 v[2:3], v[184:185]
	v_mov_b64 v[4:5], v[186:187]
	v_mov_b64 v[6:7], v[188:189]
	v_mov_b64 v[8:9], v[190:191]
	v_mov_b64 v[10:11], v[192:193]
	v_mov_b64 v[12:13], v[194:195]
	v_mov_b64 v[14:15], v[196:197]
	v_mov_b64 v[16:17], v[198:199]
.Lssd_cdone:
	v_lshl_add_u32 v18, v33, 2, v54
	ds_read_b32 v49, v18
	s_xor_b64 s[22:23], s[38:39], -1
	s_mov_b64 s[38:39], 0
	v_mov_b32_e32 v51, v76
	v_mov_b32_e32 v119, v38
	v_mov_b32_e32 v120, v78
	v_mov_b32_e32 v121, v89
	v_mov_b32_e32 v122, v88
	v_mov_b32_e32 v123, v87
	v_mov_b32_e32 v124, v86
	s_mov_b32 s3, 0
	s_branch .LBB0_629
